# moba_gate: tile of every unit in the odd 256-blocks mirrored (u^31) so a workgroup's two units have ib and 15-ib eligible blocks instead of the same ib twice
# speedup vs baseline: 1.0052x; 1.0010x over previous
.LBB0_1016:
	s_bfe_u32 s100, s17, 0x10008
	s_mul_i32 s100, s100, 31
	s_xor_b32 s17, s17, s100
	s_add_i32 s17, s17, s26
	s_cmpk_gt_i32 s17, 0x1ff
	s_waitcnt lgkmcnt(0)
	s_barrier
	s_cbranch_scc1 .LBB0_1003
.LBB0_1017:
	s_bfe_u32 s100, s17, 0x10008
	s_mul_i32 s100, s100, 31
	s_xor_b32 s17, s17, s100
	s_waitcnt vmcnt(1)
	v_mov_b32_e32 v56, v211
	s_movk_i32 s0, 0x800
	s_ashr_i32 s6, s17, 5
	v_cmp_gt_i32_e32 vcc, s0, v56
	s_and_saveexec_b64 s[0:1], vcc
	s_cbranch_execz .LBB0_1025
	v_max_i32_e32 v2, 0x600, v56
	s_ashr_i32 s7, s6, 31
	v_sub_u32_e32 v2, v2, v56
	s_lshl_b64 s[2:3], s[6:7], 13
	v_and_b32_e32 v0, 0x7f, v56
	v_add_u32_e32 v3, 0x1ff, v2
	s_movk_i32 s7, 0x1ff
	v_lshl_add_u32 v0, v0, 2, 0
	v_cmp_lt_u32_e32 vcc, s7, v3
	s_mov_b64 s[30:31], -1
	v_mov_b32_e32 v2, v56
	s_and_saveexec_b64 s[8:9], vcc
	s_cbranch_execz .LBB0_1022
	v_lshrrev_b32_e32 v2, 9, v3
	v_readlane_b32 s7, v253, 11
	v_add_u32_e32 v4, 1, v2
	s_add_u32 s30, s7, s2
	v_readlane_b32 s7, v253, 12
	v_and_b32_e32 v5, 0xfffffe, v4
	v_add_u32_e32 v57, 0x200, v56
	s_addc_u32 s31, s7, s3
	s_mov_b64 s[36:37], 0
	v_mov_b32_e32 v6, v5
	v_mov_b64_e32 v[2:3], v[56:57]
